# K=2 + early non-leader invalidate + second-to-last local arriver issues an asynchronous L2 writeback (pre-flush) so the XCD leader's buffer_wbl2 has less to write
# speedup vs baseline: 1.0035x; 1.0035x over previous
.LBB0_259:
	s_lshl_b32 s4, s97, 8
	s_add_u32 s4, s78, s4
	s_addc_u32 s5, s79, 0
	v_mov_b32_e32 v3, 0x1000
	v_mov_b32_e32 v5, 1
	global_atomic_add v5, v3, v5, s[4:5] offset:1024 sc0
	v_cvt_f32_u32_e32 v3, v4
	v_sub_u32_e32 v6, 0, v4
	v_rcp_iflag_f32_e32 v3, v3
	s_nop 0
	v_mul_f32_e32 v3, 0x4f7ffffe, v3
	v_cvt_u32_f32_e32 v3, v3
	v_mul_lo_u32 v6, v6, v3
	v_mul_hi_u32 v6, v3, v6
	v_add_u32_e32 v3, v3, v6
	s_waitcnt vmcnt(0)
	v_mul_hi_u32 v3, v5, v3
	v_mul_lo_u32 v6, v3, v4
	v_sub_u32_e32 v6, v5, v6
	v_add_u32_e32 v7, 1, v3
	v_cmp_ge_u32_e32 vcc, v6, v4
	v_add_u32_e32 v5, 1, v5
	s_nop 0
	v_cndmask_b32_e32 v3, v3, v7, vcc
	v_sub_u32_e32 v7, v6, v4
	v_cndmask_b32_e32 v6, v6, v7, vcc
	v_add_u32_e32 v7, 1, v3
	v_cmp_ge_u32_e32 vcc, v6, v4
	s_nop 1
	v_cndmask_b32_e32 v3, v3, v7, vcc
	v_mul_lo_u32 v6, v4, v3
	v_add_u32_e32 v4, v6, v4
	v_cmp_ne_u32_e32 vcc, v5, v4
	s_and_saveexec_b64 s[6:7], vcc
	s_xor_b64 s[6:7], exec, s[6:7]
	s_cbranch_execz .LBB0_273
	s_waitcnt lgkmcnt(0)
	v_add_u32_e32 v2, 1, v5
	v_cmp_eq_u32_e32 vcc, v2, v4
	s_cbranch_vccz .Lnowb_0
	buffer_wbl2 sc1
.Lnowb_0:
	buffer_inv sc1
	v_mov_b32_e32 v2, 0x2000
	global_load_dword v2, v2, s[4:5] offset:1024 sc1
	s_add_u32 s12, s4, 0x2400
	s_addc_u32 s13, s5, 0
	s_waitcnt vmcnt(0)
	v_cmp_eq_u32_e32 vcc, v2, v3
	s_and_saveexec_b64 s[10:11], vcc
	s_cbranch_execz .LBB0_272
	s_mov_b32 s30, 1
	s_mov_b64 s[16:17], 0
	v_mov_b32_e32 v2, 0
	s_branch .LBB0_263

.Lnowb_1:
	buffer_inv sc1
	v_mov_b32_e32 v2, 0x2000
	global_load_dword v2, v2, s[4:5] offset:1024 sc1
	s_add_u32 s10, s4, 0x2400
	s_addc_u32 s11, s5, 0
	s_waitcnt vmcnt(0)
	v_cmp_eq_u32_e32 vcc, v2, v3
	s_and_saveexec_b64 s[8:9], vcc
	s_cbranch_execz .LBB0_367
	s_mov_b32 s26, 1
	s_mov_b64 s[12:13], 0
	v_mov_b32_e32 v2, 0
	s_branch .LBB0_358

.Lnowb_10:
	buffer_inv sc1
	v_mov_b32_e32 v2, 0x2000
	global_load_dword v2, v2, s[4:5] offset:1024 sc1
	s_add_u32 s10, s4, 0x2400
	s_addc_u32 s11, s5, 0
	s_waitcnt vmcnt(0)
	v_cmp_eq_u32_e32 vcc, v2, v3
	s_and_saveexec_b64 s[8:9], vcc
	s_cbranch_execz .LBB0_1424
	s_mov_b32 s22, 1
	s_mov_b64 s[12:13], 0
	v_mov_b32_e32 v2, 0
	s_branch .LBB0_1415
